# Q-up epilogue stores write-back (no nt): L2 absorbs the Q image burst and attention finds the last-written Q rows in L2; no flush happens at the XCD-local seam
# speedup vs baseline: 1.0055x; 1.0055x over previous
;     __device__ __forceinline__ void operator()(const AccT& acc, const Unit& u, int wr, int wc, int fr_, int fq_) const {
;     ...
;         float ssv[2][4];
; #pragma unroll
;         for (int ai = 0; ai < 2; ++ai)
; #pragma unroll
;             for (int m = 0; m < 4; ++m) ssv[ai][m] = ssq_q[(size_t)ROW_OF(ai, m)];
; #pragma unroll
;         for (int aim = 0; aim < 4; ++aim) { const int ai = aim >> 1;
;             f32x4 cs[4][4];
;             if (pn >= 4) {
; #pragma unroll
;                 for (int m = 2 * (aim & 1); m < 2 * (aim & 1) + 2; ++m) { const f32x4* cp = (const f32x4*)(rope + (size_t)ROW_OF(ai, m) * 64 + 16 * fq);
; #pragma unroll
;                     for (int j = 0; j < 4; ++j) cs[m][j] = cp[j]; }
;             }
; #pragma unroll
;             for (int m = 2 * (aim & 1); m < 2 * (aim & 1) + 2; ++m) {
;                 const size_t row = (size_t)ROW_OF(ai, m);
;                 const float sc = QSCALE * __builtin_amdgcn_rsqf(ssv[ai][m] * (1.0f / QLORA) + EPS);
;                 const int b = (int)(row >> 11), s = (int)(row & 2047);
;                 const f32x4 a0 = acc[ai][0][m][0] * sc, a1 = acc[ai][0][m][1] * sc, b0 = acc[ai][1][m][0] * sc, b1 = acc[ai][1][m][1] * sc;
;                 if (pn < 4) {
;                     const int ks = 2 * wc + (fq >> 1), h = fq & 1;
;                     bf16_t* p = QI + ((size_t)((b * 8 + 2 * pn) * 64 + (s >> 5))) * 6144 + (ks * 2 + h) * 256 + (s & 31) * 8;
;                     st16(p, pk8(a0, a1)); st16(p + (size_t)64 * 6144, pk8(b0, b1));
;                 } else {
;                     const int head = 4 * (pn - 4) + wc;
;                     const f32x4 c0 = cs[m][0], c1 = cs[m][1], c2 = cs[m][2], c3 = cs[m][3];
;                     f32x4 o1a, o1b, o2a, o2b;
;                     o1a[0] = a0[0] * c0[0] - b0[0] * c0[1]; o2a[0] = a0[0] * c0[1] + b0[0] * c0[0];
;                     o1a[1] = a0[1] * c0[2] - b0[1] * c0[3]; o2a[1] = a0[1] * c0[3] + b0[1] * c0[2];
;                     o1a[2] = a0[2] * c1[0] - b0[2] * c1[1]; o2a[2] = a0[2] * c1[1] + b0[2] * c1[0];
;                     o1a[3] = a0[3] * c1[2] - b0[3] * c1[3]; o2a[3] = a0[3] * c1[3] + b0[3] * c1[2];
;                     o1b[0] = a1[0] * c2[0] - b1[0] * c2[1]; o2b[0] = a1[0] * c2[1] + b1[0] * c2[0];
;                     o1b[1] = a1[1] * c2[2] - b1[1] * c2[3]; o2b[1] = a1[1] * c2[3] + b1[1] * c2[2];
.LBB0_1015:
	v_lshl_add_u32 v253, s55, 8, v201
	v_add_lshl_u32 v253, v253, s45, 2
	global_load_dword v245, v253, s[90:91]
	global_load_dword v246, v253, s[90:91] offset:64
	global_load_dword v247, v253, s[90:91] offset:128
	global_load_dword v248, v253, s[90:91] offset:192
	global_load_dword v249, v253, s[90:91] offset:512
	global_load_dword v250, v253, s[90:91] offset:576
	global_load_dword v251, v253, s[90:91] offset:640
	global_load_dword v252, v253, s[90:91] offset:704
	s_waitcnt vmcnt(8)
	v_fmamk_f32 v179, v179, 0x3b2aaaab, v198
	v_rsq_f32_e32 v189, v179
	v_lshlrev_b32_e32 v168, 9, v184
	v_lshlrev_b32_e32 v178, 8, v184
	v_and_b32_e32 v168, 0x200, v168
	v_lshl_add_u64 v[182:183], s[8:9], 0, v[168:169]
	v_and_b32_e32 v168, 0xfffffe00, v178
	s_cmp_gt_i32 s28, 3
	v_add_u32_e32 v178, 0x1000, v168
	v_add_u32_e32 v180, 0x1400, v168
	v_mul_f32_e32 v168, 0x3dd53b94, v189
	s_cselect_b64 s[6:7], -1, 0
	s_lshl_b32 s4, s28, 8
	v_and_b32_e32 v191, 0x7ff, v188
	v_pk_mul_f32 v[126:127], v[126:127], v[168:169] op_sel_hi:[1,0]
	v_pk_mul_f32 v[124:125], v[124:125], v[168:169] op_sel_hi:[1,0]
	v_pk_mul_f32 v[122:123], v[122:123], v[168:169] op_sel_hi:[1,0]
	v_pk_mul_f32 v[120:121], v[120:121], v[168:169] op_sel_hi:[1,0]
	v_pk_mul_f32 v[118:119], v[118:119], v[168:169] op_sel_hi:[1,0]
	v_pk_mul_f32 v[116:117], v[116:117], v[168:169] op_sel_hi:[1,0]
	v_pk_mul_f32 v[114:115], v[114:115], v[168:169] op_sel_hi:[1,0]
	v_pk_mul_f32 v[112:113], v[112:113], v[168:169] op_sel_hi:[1,0]
	v_lshlrev_b32_e32 v168, 4, v185
	s_add_i32 s56, s47, s4
	v_ashrrev_i32_e32 v179, 31, v178
	v_ashrrev_i32_e32 v181, 31, v180
	v_ashrrev_i32_e32 v189, 11, v188
	s_mov_b64 s[4:5], -1
	s_and_b64 vcc, exec, s[6:7]
	v_lshrrev_b32_e32 v191, 5, v191
	v_and_b32_e32 v168, 0x1f0, v168
	s_cbranch_vccz .LBB0_1017
	v_mov_b32_e32 v210, v157
	v_mov_b32_e32 v211, v159
	v_mov_b32_e32 v208, v156
	v_mov_b32_e32 v209, v158
	v_pk_mul_f32 v[212:213], v[116:117], v[210:211]
	v_lshl_add_u32 v185, v189, 9, s56
	v_pk_fma_f32 v[212:213], v[124:125], v[208:209], v[212:213] neg_lo:[0,0,1] neg_hi:[0,0,1]
	v_pk_mul_f32 v[208:209], v[116:117], v[208:209]
	v_or_b32_e32 v185, v185, v191
	v_pk_fma_f32 v[214:215], v[124:125], v[210:211], v[208:209]
	v_mov_b32_e32 v210, v153
	v_mov_b32_e32 v211, v155
	v_mov_b32_e32 v208, v152
	v_mov_b32_e32 v209, v154
	v_pk_mul_f32 v[216:217], v[118:119], v[210:211]
	s_nop 0
	v_pk_fma_f32 v[216:217], v[126:127], v[208:209], v[216:217] neg_lo:[0,0,1] neg_hi:[0,0,1]
	v_pk_mul_f32 v[208:209], v[118:119], v[208:209]
	s_nop 0
	v_pk_fma_f32 v[218:219], v[126:127], v[210:211], v[208:209]
	v_mov_b32_e32 v210, v149
	v_mov_b32_e32 v211, v151
	v_mov_b32_e32 v208, v148
	v_mov_b32_e32 v209, v150
	v_pk_mul_f32 v[220:221], v[112:113], v[210:211]
	s_nop 0
	v_pk_fma_f32 v[220:221], v[120:121], v[208:209], v[220:221] neg_lo:[0,0,1] neg_hi:[0,0,1]
	v_pk_mul_f32 v[208:209], v[112:113], v[208:209]
	s_nop 0
	v_pk_fma_f32 v[222:223], v[120:121], v[210:211], v[208:209]
	v_mov_b32_e32 v210, v145
	v_mov_b32_e32 v211, v147
	v_mov_b32_e32 v208, v144
	v_mov_b32_e32 v209, v146
	v_pk_mul_f32 v[224:225], v[114:115], v[210:211]
	s_nop 0
	v_pk_fma_f32 v[224:225], v[122:123], v[208:209], v[224:225] neg_lo:[0,0,1] neg_hi:[0,0,1]
	v_pk_mul_f32 v[208:209], v[114:115], v[208:209]
	s_nop 0
	v_pk_fma_f32 v[226:227], v[122:123], v[210:211], v[208:209]
	v_mad_i64_i32 v[208:209], s[4:5], v185, s54, v[182:183]
	v_lshl_add_u64 v[228:229], v[208:209], 0, v[168:169]
	v_lshl_add_u64 v[230:231], v[178:179], 1, v[228:229]
	v_cvt_pk_bf16_f32 v208, v212, v213
	v_cvt_pk_bf16_f32 v209, v216, v217
	v_cvt_pk_bf16_f32 v210, v220, v221
	v_cvt_pk_bf16_f32 v211, v224, v225
	global_store_dwordx4 v[230:231], v[208:211], off
	v_lshl_add_u64 v[212:213], v[180:181], 1, v[228:229]
	s_mov_b64 s[4:5], 0
	v_cvt_pk_bf16_f32 v208, v214, v215
	v_cvt_pk_bf16_f32 v209, v218, v219
	v_cvt_pk_bf16_f32 v210, v222, v223
	v_cvt_pk_bf16_f32 v211, v226, v227
	global_store_dwordx4 v[212:213], v[208:211], off
; __device__ __forceinline__ u32x4 pk8(f32x4 a, f32x4 b) { u32x4 w; w.x = pk2(a[0], a[1]); w.y = pk2(a[2], a[3]); w.z = pk2(b[0], b[1]); w.w = pk2(b[2], b[3]); return w; }
;     __device__ __forceinline__ void operator()(const AccT& acc, const Unit& u, int wr, int wc, int fr_, int fq_) const {
;     ...
;             for (int m = 2 * (aim & 1); m < 2 * (aim & 1) + 2; ++m) {
;                 const size_t row = (size_t)ROW_OF(ai, m);
;                 const float sc = QSCALE * __builtin_amdgcn_rsqf(ssv[ai][m] * (1.0f / QLORA) + EPS);
;                 const int b = (int)(row >> 11), s = (int)(row & 2047);
;                 const f32x4 a0 = acc[ai][0][m][0] * sc, a1 = acc[ai][0][m][1] * sc, b0 = acc[ai][1][m][0] * sc, b1 = acc[ai][1][m][1] * sc;
;                 if (pn < 4) {
;                     const int ks = 2 * wc + (fq >> 1), h = fq & 1;
;                     bf16_t* p = QI + ((size_t)((b * 8 + 2 * pn) * 64 + (s >> 5))) * 6144 + (ks * 2 + h) * 256 + (s & 31) * 8;
;                     st16(p, pk8(a0, a1)); st16(p + (size_t)64 * 6144, pk8(b0, b1));
;                 } else {
;                     const int head = 4 * (pn - 4) + wc;
;                     const f32x4 c0 = cs[m][0], c1 = cs[m][1], c2 = cs[m][2], c3 = cs[m][3];
;                     f32x4 o1a, o1b, o2a, o2b;
;                     o1a[0] = a0[0] * c0[0] - b0[0] * c0[1]; o2a[0] = a0[0] * c0[1] + b0[0] * c0[0];
;                     o1a[1] = a0[1] * c0[2] - b0[1] * c0[3]; o2a[1] = a0[1] * c0[3] + b0[1] * c0[2];
;                     o1a[2] = a0[2] * c1[0] - b0[2] * c1[1]; o2a[2] = a0[2] * c1[1] + b0[2] * c1[0];
;                     o1a[3] = a0[3] * c1[2] - b0[3] * c1[3]; o2a[3] = a0[3] * c1[3] + b0[3] * c1[2];
;                     o1b[0] = a1[0] * c2[0] - b1[0] * c2[1]; o2b[0] = a1[0] * c2[1] + b1[0] * c2[0];
;                     o1b[1] = a1[1] * c2[2] - b1[1] * c2[3]; o2b[1] = a1[1] * c2[3] + b1[1] * c2[2];
;                     o1b[2] = a1[2] * c3[0] - b1[2] * c3[1]; o2b[2] = a1[2] * c3[1] + b1[2] * c3[0];
;                     o1b[3] = a1[3] * c3[2] - b1[3] * c3[3]; o2b[3] = a1[3] * c3[3] + b1[3] * c3[2];
;                     bf16_t* p = QI + ((size_t)((b * 8 + head) * 64 + (s >> 5))) * 6144 + (fq & 1) * 256 + (s & 31) * 8;
;                     st16(p + (8 + (fq >> 1)) * 512, pk8(o1a, o1b)); st16(p + (10 + (fq >> 1)) * 512, pk8(o2a, o2b));
;                 }
.LBB0_1017:
	v_and_b32_e32 v185, 0xfffffe, v184
	v_add_u32_e32 v185, s48, v185
	v_and_or_b32 v184, v184, 1, v185
	v_lshlrev_b32_e32 v184, 8, v184
	v_ashrrev_i32_e32 v185, 31, v184
	s_lshl_b32 s57, s28, 7
	s_andn2_b64 vcc, exec, s[4:5]
	v_lshl_add_u64 v[184:185], v[184:185], 1, s[8:9]
	s_cbranch_vccnz .LBB0_1019
	v_lshl_add_u32 v189, v189, 9, s57
	v_or_b32_e32 v189, v189, v191
	v_mad_i64_i32 v[208:209], s[4:5], v189, s54, v[184:185]
	v_lshl_add_u64 v[208:209], v[208:209], 0, v[168:169]
	v_cvt_pk_bf16_f32 v116, v116, v117
	v_cvt_pk_bf16_f32 v117, v118, v119
	v_cvt_pk_bf16_f32 v118, v112, v113
	v_add_co_u32_e32 v112, vcc, 0xc0000, v208
	v_cvt_pk_bf16_f32 v124, v124, v125
	v_cvt_pk_bf16_f32 v125, v126, v127
	v_cvt_pk_bf16_f32 v126, v120, v121
	v_cvt_pk_bf16_f32 v127, v122, v123
	v_cvt_pk_bf16_f32 v119, v114, v115
	v_addc_co_u32_e32 v113, vcc, 0, v209, vcc
	global_store_dwordx4 v[208:209], v[124:127], off
	global_store_dwordx4 v[112:113], v[116:119], off
.LBB0_1019:
	v_fmamk_f32 v112, v192, 0x3b2aaaab, v198
	v_rsq_f32_e32 v113, v112
	v_and_b32_e32 v115, 0x7ff, v190
	v_ashrrev_i32_e32 v112, 11, v190
	s_mov_b64 s[28:29], -1
	v_mul_f32_e32 v114, 0x3dd53b94, v113
	v_cndmask_b32_e64 v113, 0, 1, s[6:7]
	v_pk_mul_f32 v[110:111], v[110:111], v[114:115] op_sel_hi:[1,0]
	v_pk_mul_f32 v[108:109], v[108:109], v[114:115] op_sel_hi:[1,0]
	v_pk_mul_f32 v[106:107], v[106:107], v[114:115] op_sel_hi:[1,0]
	v_pk_mul_f32 v[104:105], v[104:105], v[114:115] op_sel_hi:[1,0]
	v_pk_mul_f32 v[102:103], v[102:103], v[114:115] op_sel_hi:[1,0]
	v_pk_mul_f32 v[100:101], v[100:101], v[114:115] op_sel_hi:[1,0]
	v_pk_mul_f32 v[98:99], v[98:99], v[114:115] op_sel_hi:[1,0]
	v_pk_mul_f32 v[96:97], v[96:97], v[114:115] op_sel_hi:[1,0]
	v_cmp_ne_u32_e64 s[4:5], 1, v113
	s_andn2_b64 vcc, exec, s[6:7]
	v_lshrrev_b32_e32 v114, 5, v115
	v_lshlrev_b32_e32 v113, 4, v190
	s_cbranch_vccnz .LBB0_1021
	v_mov_b32_e32 v118, v141
	v_mov_b32_e32 v119, v143
	v_mov_b32_e32 v116, v140
	v_mov_b32_e32 v117, v142
	v_pk_mul_f32 v[120:121], v[100:101], v[118:119]
	v_lshl_add_u32 v115, v112, 9, s56
	v_pk_fma_f32 v[120:121], v[108:109], v[116:117], v[120:121] neg_lo:[0,0,1] neg_hi:[0,0,1]
	v_pk_mul_f32 v[116:117], v[100:101], v[116:117]
	v_or_b32_e32 v115, v115, v114
	v_pk_fma_f32 v[122:123], v[108:109], v[118:119], v[116:117]
	v_mov_b32_e32 v118, v137
	v_mov_b32_e32 v119, v139
	v_mov_b32_e32 v116, v136
	v_mov_b32_e32 v117, v138
	v_pk_mul_f32 v[124:125], v[102:103], v[118:119]
	s_mov_b64 s[28:29], 0
	v_pk_fma_f32 v[124:125], v[110:111], v[116:117], v[124:125] neg_lo:[0,0,1] neg_hi:[0,0,1]
	v_pk_mul_f32 v[116:117], v[102:103], v[116:117]
	s_nop 0
	v_pk_fma_f32 v[126:127], v[110:111], v[118:119], v[116:117]
	v_mov_b32_e32 v118, v133
	v_mov_b32_e32 v119, v135
	v_mov_b32_e32 v116, v132
	v_mov_b32_e32 v117, v134
	v_pk_mul_f32 v[190:191], v[96:97], v[118:119]
	s_nop 0
	v_pk_fma_f32 v[190:191], v[104:105], v[116:117], v[190:191] neg_lo:[0,0,1] neg_hi:[0,0,1]
	v_pk_mul_f32 v[116:117], v[96:97], v[116:117]
	s_nop 0
	v_pk_fma_f32 v[192:193], v[104:105], v[118:119], v[116:117]
	v_mov_b32_e32 v118, v129
	v_mov_b32_e32 v119, v131
	v_mov_b32_e32 v116, v128
	v_mov_b32_e32 v117, v130
	v_pk_mul_f32 v[208:209], v[98:99], v[118:119]
	s_nop 0
	v_pk_fma_f32 v[208:209], v[106:107], v[116:117], v[208:209] neg_lo:[0,0,1] neg_hi:[0,0,1]
	v_pk_mul_f32 v[116:117], v[98:99], v[116:117]
	s_nop 0
	v_pk_fma_f32 v[210:211], v[106:107], v[118:119], v[116:117]
	v_mad_i64_i32 v[116:117], s[6:7], v115, s54, v[182:183]
	v_and_b32_e32 v118, 0x1f0, v113
	v_mov_b32_e32 v119, v169
	v_lshl_add_u64 v[212:213], v[116:117], 0, v[118:119]
	v_lshl_add_u64 v[214:215], v[178:179], 1, v[212:213]
	v_cvt_pk_bf16_f32 v116, v120, v121
	v_cvt_pk_bf16_f32 v117, v124, v125
	v_cvt_pk_bf16_f32 v118, v190, v191
	v_cvt_pk_bf16_f32 v119, v208, v209
	global_store_dwordx4 v[214:215], v[116:119], off
	v_lshl_add_u64 v[120:121], v[180:181], 1, v[212:213]
	s_nop 0
	v_cvt_pk_bf16_f32 v116, v122, v123
	v_cvt_pk_bf16_f32 v117, v126, v127
	v_cvt_pk_bf16_f32 v118, v192, v193
	v_cvt_pk_bf16_f32 v119, v210, v211
	global_store_dwordx4 v[120:121], v[116:119], off
.LBB0_1021:
	s_andn2_b64 vcc, exec, s[28:29]
	s_cbranch_vccnz .LBB0_1023
	v_lshl_add_u32 v112, v112, 9, s57
	v_or_b32_e32 v112, v112, v114
	v_mad_i64_i32 v[114:115], s[6:7], v112, s54, v[184:185]
	v_and_b32_e32 v112, 0x1f0, v113
	v_mov_b32_e32 v113, v169
	v_lshl_add_u64 v[112:113], v[114:115], 0, v[112:113]
	v_cvt_pk_bf16_f32 v100, v100, v101
	v_cvt_pk_bf16_f32 v101, v102, v103
	v_cvt_pk_bf16_f32 v102, v96, v97
	v_add_co_u32_e32 v96, vcc, 0xc0000, v112
	v_cvt_pk_bf16_f32 v108, v108, v109
	v_cvt_pk_bf16_f32 v109, v110, v111
	v_cvt_pk_bf16_f32 v110, v104, v105
	v_cvt_pk_bf16_f32 v111, v106, v107
	v_cvt_pk_bf16_f32 v103, v98, v99
	v_addc_co_u32_e32 v97, vcc, 0, v113, vcc
	global_store_dwordx4 v[112:113], v[108:111], off
	global_store_dwordx4 v[96:97], v[100:103], off

; __device__ __forceinline__ u32x4 pk8(f32x4 a, f32x4 b) { u32x4 w; w.x = pk2(a[0], a[1]); w.y = pk2(a[2], a[3]); w.z = pk2(b[0], b[1]); w.w = pk2(b[2], b[3]); return w; }
;     __device__ __forceinline__ void operator()(const AccT& acc, const Unit& u, int wr, int wc, int fr_, int fq_) const {
;     ...
;             for (int m = 2 * (aim & 1); m < 2 * (aim & 1) + 2; ++m) {
;                 const size_t row = (size_t)ROW_OF(ai, m);
;                 const float sc = QSCALE * __builtin_amdgcn_rsqf(ssv[ai][m] * (1.0f / QLORA) + EPS);
;                 const int b = (int)(row >> 11), s = (int)(row & 2047);
;                 const f32x4 a0 = acc[ai][0][m][0] * sc, a1 = acc[ai][0][m][1] * sc, b0 = acc[ai][1][m][0] * sc, b1 = acc[ai][1][m][1] * sc;
;                 if (pn < 4) {
;                     const int ks = 2 * wc + (fq >> 1), h = fq & 1;
;                     bf16_t* p = QI + ((size_t)((b * 8 + 2 * pn) * 64 + (s >> 5))) * 6144 + (ks * 2 + h) * 256 + (s & 31) * 8;
;                     st16(p, pk8(a0, a1)); st16(p + (size_t)64 * 6144, pk8(b0, b1));
;                 } else {
;                     const int head = 4 * (pn - 4) + wc;
;                     const f32x4 c0 = cs[m][0], c1 = cs[m][1], c2 = cs[m][2], c3 = cs[m][3];
;                     f32x4 o1a, o1b, o2a, o2b;
;                     o1a[0] = a0[0] * c0[0] - b0[0] * c0[1]; o2a[0] = a0[0] * c0[1] + b0[0] * c0[0];
;                     o1a[1] = a0[1] * c0[2] - b0[1] * c0[3]; o2a[1] = a0[1] * c0[3] + b0[1] * c0[2];
;                     o1a[2] = a0[2] * c1[0] - b0[2] * c1[1]; o2a[2] = a0[2] * c1[1] + b0[2] * c1[0];
;                     o1a[3] = a0[3] * c1[2] - b0[3] * c1[3]; o2a[3] = a0[3] * c1[3] + b0[3] * c1[2];
;                     o1b[0] = a1[0] * c2[0] - b1[0] * c2[1]; o2b[0] = a1[0] * c2[1] + b1[0] * c2[0];
;                     o1b[1] = a1[1] * c2[2] - b1[1] * c2[3]; o2b[1] = a1[1] * c2[3] + b1[1] * c2[2];
;                     o1b[2] = a1[2] * c3[0] - b1[2] * c3[1]; o2b[2] = a1[2] * c3[1] + b1[2] * c3[0];
;                     o1b[3] = a1[3] * c3[2] - b1[3] * c3[3]; o2b[3] = a1[3] * c3[3] + b1[3] * c3[2];
;                     bf16_t* p = QI + ((size_t)((b * 8 + head) * 64 + (s >> 5))) * 6144 + (fq & 1) * 256 + (s & 31) * 8;
;                     st16(p + (8 + (fq >> 1)) * 512, pk8(o1a, o1b)); st16(p + (10 + (fq >> 1)) * 512, pk8(o2a, o2b));
;                 }
.LBB0_1025:
	v_fmamk_f32 v189, v206, 0x3b2aaaab, v198
	v_rsq_f32_e32 v191, v189
	v_ashrrev_i32_e32 v189, 11, v192
	v_and_b32_e32 v193, 0x7ff, v192
	s_mov_b64 s[10:11], -1
	v_mul_f32_e32 v192, 0x3dd53b94, v191
	v_pk_mul_f32 v[94:95], v[94:95], v[192:193] op_sel_hi:[1,0]
	v_pk_mul_f32 v[92:93], v[92:93], v[192:193] op_sel_hi:[1,0]
	v_pk_mul_f32 v[90:91], v[90:91], v[192:193] op_sel_hi:[1,0]
	v_pk_mul_f32 v[88:89], v[88:89], v[192:193] op_sel_hi:[1,0]
	v_pk_mul_f32 v[86:87], v[86:87], v[192:193] op_sel_hi:[1,0]
	v_pk_mul_f32 v[84:85], v[84:85], v[192:193] op_sel_hi:[1,0]
	v_pk_mul_f32 v[82:83], v[82:83], v[192:193] op_sel_hi:[1,0]
	v_pk_mul_f32 v[80:81], v[80:81], v[192:193] op_sel_hi:[1,0]
	s_and_b64 vcc, exec, s[4:5]
	v_lshrrev_b32_e32 v191, 5, v193
	s_cbranch_vccnz .LBB0_1027
	s_waitcnt vmcnt(0)
	v_mov_b32_e32 v206, v125
	v_mov_b32_e32 v207, v127
	v_mov_b32_e32 v192, v124
	v_mov_b32_e32 v193, v126
	v_pk_mul_f32 v[208:209], v[84:85], v[206:207]
	v_mov_b32_e32 v210, v121
	v_pk_fma_f32 v[208:209], v[92:93], v[192:193], v[208:209] neg_lo:[0,0,1] neg_hi:[0,0,1]
	v_pk_mul_f32 v[192:193], v[84:85], v[192:193]
	v_mov_b32_e32 v211, v123
	v_pk_fma_f32 v[192:193], v[92:93], v[206:207], v[192:193]
	v_mov_b32_e32 v206, v120
	v_mov_b32_e32 v207, v122
	v_pk_mul_f32 v[212:213], v[86:87], v[210:211]
	v_mov_b32_e32 v214, v117
	v_pk_fma_f32 v[212:213], v[94:95], v[206:207], v[212:213] neg_lo:[0,0,1] neg_hi:[0,0,1]
	v_pk_mul_f32 v[206:207], v[86:87], v[206:207]
	v_mov_b32_e32 v215, v119
	v_pk_fma_f32 v[210:211], v[94:95], v[210:211], v[206:207]
	v_mov_b32_e32 v206, v116
	v_mov_b32_e32 v207, v118
	v_pk_mul_f32 v[216:217], v[80:81], v[214:215]
	v_mov_b32_e32 v218, v113
	v_pk_fma_f32 v[216:217], v[88:89], v[206:207], v[216:217] neg_lo:[0,0,1] neg_hi:[0,0,1]
	v_pk_mul_f32 v[206:207], v[80:81], v[206:207]
	v_mov_b32_e32 v219, v115
	v_pk_fma_f32 v[214:215], v[88:89], v[214:215], v[206:207]
	v_mov_b32_e32 v206, v112
	v_mov_b32_e32 v207, v114
	v_pk_mul_f32 v[220:221], v[82:83], v[218:219]
	s_nop 0
	v_pk_fma_f32 v[220:221], v[90:91], v[206:207], v[220:221] neg_lo:[0,0,1] neg_hi:[0,0,1]
	v_pk_mul_f32 v[206:207], v[82:83], v[206:207]
	s_nop 0
	v_pk_fma_f32 v[218:219], v[90:91], v[218:219], v[206:207]
	v_lshl_add_u32 v206, v189, 9, s56
	v_or_b32_e32 v206, v206, v191
	v_mad_i64_i32 v[206:207], s[10:11], v206, s54, v[182:183]
	v_lshl_add_u64 v[222:223], v[206:207], 0, v[168:169]
	v_lshl_add_u64 v[224:225], v[178:179], 1, v[222:223]
	v_cvt_pk_bf16_f32 v206, v208, v209
	v_cvt_pk_bf16_f32 v207, v212, v213
	v_cvt_pk_bf16_f32 v208, v216, v217
	v_cvt_pk_bf16_f32 v209, v220, v221
	global_store_dwordx4 v[224:225], v[206:209], off
	v_lshl_add_u64 v[212:213], v[180:181], 1, v[222:223]
	s_mov_b64 s[10:11], 0
	v_cvt_pk_bf16_f32 v206, v192, v193
	v_cvt_pk_bf16_f32 v207, v210, v211
	v_cvt_pk_bf16_f32 v208, v214, v215
	v_cvt_pk_bf16_f32 v209, v218, v219
	global_store_dwordx4 v[212:213], v[206:209], off
.LBB0_1027:
	s_andn2_b64 vcc, exec, s[10:11]
	s_cbranch_vccnz .LBB0_1029
	v_lshl_add_u32 v189, v189, 9, s57
	v_or_b32_e32 v189, v189, v191
	v_mad_i64_i32 v[192:193], s[10:11], v189, s54, v[184:185]
	v_lshl_add_u64 v[192:193], v[192:193], 0, v[168:169]
	v_cvt_pk_bf16_f32 v84, v84, v85
	v_cvt_pk_bf16_f32 v85, v86, v87
	v_cvt_pk_bf16_f32 v86, v80, v81
	v_add_co_u32_e32 v80, vcc, 0xc0000, v192
	v_cvt_pk_bf16_f32 v92, v92, v93
	v_cvt_pk_bf16_f32 v93, v94, v95
	v_cvt_pk_bf16_f32 v94, v88, v89
	v_cvt_pk_bf16_f32 v95, v90, v91
	v_cvt_pk_bf16_f32 v87, v82, v83
	v_addc_co_u32_e32 v81, vcc, 0, v193, vcc
	global_store_dwordx4 v[192:193], v[92:95], off
	global_store_dwordx4 v[80:81], v[84:87], off
; __device__ __forceinline__ u32x4 pk8(f32x4 a, f32x4 b) { u32x4 w; w.x = pk2(a[0], a[1]); w.y = pk2(a[2], a[3]); w.z = pk2(b[0], b[1]); w.w = pk2(b[2], b[3]); return w; }
;     __device__ __forceinline__ void operator()(const AccT& acc, const Unit& u, int wr, int wc, int fr_, int fq_) const {
;     ...
;             for (int m = 2 * (aim & 1); m < 2 * (aim & 1) + 2; ++m) {
;                 const size_t row = (size_t)ROW_OF(ai, m);
;                 const float sc = QSCALE * __builtin_amdgcn_rsqf(ssv[ai][m] * (1.0f / QLORA) + EPS);
;                 const int b = (int)(row >> 11), s = (int)(row & 2047);
;                 const f32x4 a0 = acc[ai][0][m][0] * sc, a1 = acc[ai][0][m][1] * sc, b0 = acc[ai][1][m][0] * sc, b1 = acc[ai][1][m][1] * sc;
;                 if (pn < 4) {
;                     const int ks = 2 * wc + (fq >> 1), h = fq & 1;
;                     bf16_t* p = QI + ((size_t)((b * 8 + 2 * pn) * 64 + (s >> 5))) * 6144 + (ks * 2 + h) * 256 + (s & 31) * 8;
;                     st16(p, pk8(a0, a1)); st16(p + (size_t)64 * 6144, pk8(b0, b1));
;                 } else {
;                     const int head = 4 * (pn - 4) + wc;
;                     const f32x4 c0 = cs[m][0], c1 = cs[m][1], c2 = cs[m][2], c3 = cs[m][3];
;                     f32x4 o1a, o1b, o2a, o2b;
;                     o1a[0] = a0[0] * c0[0] - b0[0] * c0[1]; o2a[0] = a0[0] * c0[1] + b0[0] * c0[0];
;                     o1a[1] = a0[1] * c0[2] - b0[1] * c0[3]; o2a[1] = a0[1] * c0[3] + b0[1] * c0[2];
;                     o1a[2] = a0[2] * c1[0] - b0[2] * c1[1]; o2a[2] = a0[2] * c1[1] + b0[2] * c1[0];
;                     o1a[3] = a0[3] * c1[2] - b0[3] * c1[3]; o2a[3] = a0[3] * c1[3] + b0[3] * c1[2];
;                     o1b[0] = a1[0] * c2[0] - b1[0] * c2[1]; o2b[0] = a1[0] * c2[1] + b1[0] * c2[0];
;                     o1b[1] = a1[1] * c2[2] - b1[1] * c2[3]; o2b[1] = a1[1] * c2[3] + b1[1] * c2[2];
;                     o1b[2] = a1[2] * c3[0] - b1[2] * c3[1]; o2b[2] = a1[2] * c3[1] + b1[2] * c3[0];
;                     o1b[3] = a1[3] * c3[2] - b1[3] * c3[3]; o2b[3] = a1[3] * c3[3] + b1[3] * c3[2];
;                     bf16_t* p = QI + ((size_t)((b * 8 + head) * 64 + (s >> 5))) * 6144 + (fq & 1) * 256 + (s & 31) * 8;
;                     st16(p + (8 + (fq >> 1)) * 512, pk8(o1a, o1b)); st16(p + (10 + (fq >> 1)) * 512, pk8(o2a, o2b));
;                 }
.LBB0_1029:
	v_fmamk_f32 v80, v205, 0x3b2aaaab, v198
	v_rsq_f32_e32 v81, v80
	v_and_b32_e32 v83, 0x7ff, v190
	v_ashrrev_i32_e32 v80, 11, v190
	s_mov_b64 s[10:11], -1
	v_mul_f32_e32 v82, 0x3dd53b94, v81
	v_pk_mul_f32 v[78:79], v[78:79], v[82:83] op_sel_hi:[1,0]
	v_pk_mul_f32 v[76:77], v[76:77], v[82:83] op_sel_hi:[1,0]
	v_pk_mul_f32 v[74:75], v[74:75], v[82:83] op_sel_hi:[1,0]
	v_pk_mul_f32 v[72:73], v[72:73], v[82:83] op_sel_hi:[1,0]
	v_pk_mul_f32 v[70:71], v[70:71], v[82:83] op_sel_hi:[1,0]
	v_pk_mul_f32 v[68:69], v[68:69], v[82:83] op_sel_hi:[1,0]
	v_pk_mul_f32 v[66:67], v[66:67], v[82:83] op_sel_hi:[1,0]
	v_pk_mul_f32 v[64:65], v[64:65], v[82:83] op_sel_hi:[1,0]
	s_and_b64 vcc, exec, s[4:5]
	v_lshrrev_b32_e32 v82, 5, v83
	v_lshlrev_b32_e32 v81, 4, v190
	s_cbranch_vccnz .LBB0_1031
	s_waitcnt vmcnt(0)
	v_mov_b32_e32 v86, v109
	v_mov_b32_e32 v87, v111
	v_mov_b32_e32 v84, v108
	v_mov_b32_e32 v85, v110
	v_pk_mul_f32 v[88:89], v[68:69], v[86:87]
	v_lshl_add_u32 v83, v80, 9, s56
	v_pk_fma_f32 v[88:89], v[76:77], v[84:85], v[88:89] neg_lo:[0,0,1] neg_hi:[0,0,1]
	v_pk_mul_f32 v[84:85], v[68:69], v[84:85]
	v_or_b32_e32 v83, v83, v82
	v_pk_fma_f32 v[90:91], v[76:77], v[86:87], v[84:85]
	v_mov_b32_e32 v86, v105
	v_mov_b32_e32 v87, v107
	v_mov_b32_e32 v84, v104
	v_mov_b32_e32 v85, v106
	v_pk_mul_f32 v[92:93], v[70:71], v[86:87]
	s_nop 0
	v_pk_fma_f32 v[92:93], v[78:79], v[84:85], v[92:93] neg_lo:[0,0,1] neg_hi:[0,0,1]
	v_pk_mul_f32 v[84:85], v[70:71], v[84:85]
	s_nop 0
	v_pk_fma_f32 v[94:95], v[78:79], v[86:87], v[84:85]
	v_mov_b32_e32 v86, v101
	v_mov_b32_e32 v87, v103
	v_mov_b32_e32 v84, v100
	v_mov_b32_e32 v85, v102
	v_pk_mul_f32 v[190:191], v[64:65], v[86:87]
	s_nop 0
	v_pk_fma_f32 v[190:191], v[72:73], v[84:85], v[190:191] neg_lo:[0,0,1] neg_hi:[0,0,1]
	v_pk_mul_f32 v[84:85], v[64:65], v[84:85]
	s_nop 0
	v_pk_fma_f32 v[192:193], v[72:73], v[86:87], v[84:85]
	v_mov_b32_e32 v86, v97
	v_mov_b32_e32 v87, v99
	v_mov_b32_e32 v84, v96
	v_mov_b32_e32 v85, v98
	v_pk_mul_f32 v[206:207], v[66:67], v[86:87]
	s_nop 0
	v_pk_fma_f32 v[206:207], v[74:75], v[84:85], v[206:207] neg_lo:[0,0,1] neg_hi:[0,0,1]
	v_pk_mul_f32 v[84:85], v[66:67], v[84:85]
	s_nop 0
	v_pk_fma_f32 v[208:209], v[74:75], v[86:87], v[84:85]
	v_mad_i64_i32 v[84:85], s[10:11], v83, s54, v[182:183]
	v_and_b32_e32 v86, 0x1f0, v81
	v_mov_b32_e32 v87, v169
	v_lshl_add_u64 v[210:211], v[84:85], 0, v[86:87]
	v_lshl_add_u64 v[212:213], v[178:179], 1, v[210:211]
	v_cvt_pk_bf16_f32 v84, v88, v89
	v_cvt_pk_bf16_f32 v85, v92, v93
	v_cvt_pk_bf16_f32 v86, v190, v191
	v_cvt_pk_bf16_f32 v87, v206, v207
	global_store_dwordx4 v[212:213], v[84:87], off
	v_lshl_add_u64 v[88:89], v[180:181], 1, v[210:211]
	s_mov_b64 s[10:11], 0
	v_cvt_pk_bf16_f32 v84, v90, v91
	v_cvt_pk_bf16_f32 v85, v94, v95
	v_cvt_pk_bf16_f32 v86, v192, v193
	v_cvt_pk_bf16_f32 v87, v208, v209
	global_store_dwordx4 v[88:89], v[84:87], off
.LBB0_1031:
	s_andn2_b64 vcc, exec, s[10:11]
	s_cbranch_vccnz .LBB0_1033
	v_lshl_add_u32 v80, v80, 9, s57
	v_or_b32_e32 v80, v80, v82
	v_mad_i64_i32 v[82:83], s[10:11], v80, s54, v[184:185]
	v_and_b32_e32 v80, 0x1f0, v81
	v_mov_b32_e32 v81, v169
	v_lshl_add_u64 v[80:81], v[82:83], 0, v[80:81]
	v_cvt_pk_bf16_f32 v68, v68, v69
	v_cvt_pk_bf16_f32 v69, v70, v71
	v_cvt_pk_bf16_f32 v70, v64, v65
	v_add_co_u32_e32 v64, vcc, 0xc0000, v80
	v_cvt_pk_bf16_f32 v76, v76, v77
	v_cvt_pk_bf16_f32 v77, v78, v79
	v_cvt_pk_bf16_f32 v78, v72, v73
	v_cvt_pk_bf16_f32 v79, v74, v75
	v_cvt_pk_bf16_f32 v71, v66, v67
	v_addc_co_u32_e32 v65, vcc, 0, v81, vcc
	global_store_dwordx4 v[80:81], v[76:79], off
	global_store_dwordx4 v[64:65], v[68:71], off

; __device__ __forceinline__ u32x4 pk8(f32x4 a, f32x4 b) { u32x4 w; w.x = pk2(a[0], a[1]); w.y = pk2(a[2], a[3]); w.z = pk2(b[0], b[1]); w.w = pk2(b[2], b[3]); return w; }
;     __device__ __forceinline__ void operator()(const AccT& acc, const Unit& u, int wr, int wc, int fr_, int fq_) const {
;     ...
;             for (int m = 2 * (aim & 1); m < 2 * (aim & 1) + 2; ++m) {
;                 const size_t row = (size_t)ROW_OF(ai, m);
;                 const float sc = QSCALE * __builtin_amdgcn_rsqf(ssv[ai][m] * (1.0f / QLORA) + EPS);
;                 const int b = (int)(row >> 11), s = (int)(row & 2047);
;                 const f32x4 a0 = acc[ai][0][m][0] * sc, a1 = acc[ai][0][m][1] * sc, b0 = acc[ai][1][m][0] * sc, b1 = acc[ai][1][m][1] * sc;
;                 if (pn < 4) {
;                     const int ks = 2 * wc + (fq >> 1), h = fq & 1;
;                     bf16_t* p = QI + ((size_t)((b * 8 + 2 * pn) * 64 + (s >> 5))) * 6144 + (ks * 2 + h) * 256 + (s & 31) * 8;
;                     st16(p, pk8(a0, a1)); st16(p + (size_t)64 * 6144, pk8(b0, b1));
;                 } else {
;                     const int head = 4 * (pn - 4) + wc;
;                     const f32x4 c0 = cs[m][0], c1 = cs[m][1], c2 = cs[m][2], c3 = cs[m][3];
;                     f32x4 o1a, o1b, o2a, o2b;
;                     o1a[0] = a0[0] * c0[0] - b0[0] * c0[1]; o2a[0] = a0[0] * c0[1] + b0[0] * c0[0];
;                     o1a[1] = a0[1] * c0[2] - b0[1] * c0[3]; o2a[1] = a0[1] * c0[3] + b0[1] * c0[2];
;                     o1a[2] = a0[2] * c1[0] - b0[2] * c1[1]; o2a[2] = a0[2] * c1[1] + b0[2] * c1[0];
;                     o1a[3] = a0[3] * c1[2] - b0[3] * c1[3]; o2a[3] = a0[3] * c1[3] + b0[3] * c1[2];
;                     o1b[0] = a1[0] * c2[0] - b1[0] * c2[1]; o2b[0] = a1[0] * c2[1] + b1[0] * c2[0];
;                     o1b[1] = a1[1] * c2[2] - b1[1] * c2[3]; o2b[1] = a1[1] * c2[3] + b1[1] * c2[2];
;                     o1b[2] = a1[2] * c3[0] - b1[2] * c3[1]; o2b[2] = a1[2] * c3[1] + b1[2] * c3[0];
;                     o1b[3] = a1[3] * c3[2] - b1[3] * c3[3]; o2b[3] = a1[3] * c3[3] + b1[3] * c3[2];
;                     bf16_t* p = QI + ((size_t)((b * 8 + head) * 64 + (s >> 5))) * 6144 + (fq & 1) * 256 + (s & 31) * 8;
;                     st16(p + (8 + (fq >> 1)) * 512, pk8(o1a, o1b)); st16(p + (10 + (fq >> 1)) * 512, pk8(o2a, o2b));
;                 }
.LBB0_1035:
	v_fmamk_f32 v65, v204, 0x3b2aaaab, v198
	v_rsq_f32_e32 v67, v65
	v_ashrrev_i32_e32 v65, 11, v66
	v_and_b32_e32 v68, 0x7ff, v66
	s_mov_b64 s[10:11], -1
	v_mul_f32_e32 v66, 0x3dd53b94, v67
	v_pk_mul_f32 v[62:63], v[62:63], v[66:67] op_sel_hi:[1,0]
	v_pk_mul_f32 v[60:61], v[60:61], v[66:67] op_sel_hi:[1,0]
	v_pk_mul_f32 v[58:59], v[58:59], v[66:67] op_sel_hi:[1,0]
	v_pk_mul_f32 v[56:57], v[56:57], v[66:67] op_sel_hi:[1,0]
	v_pk_mul_f32 v[54:55], v[54:55], v[66:67] op_sel_hi:[1,0]
	v_pk_mul_f32 v[52:53], v[52:53], v[66:67] op_sel_hi:[1,0]
	v_pk_mul_f32 v[50:51], v[50:51], v[66:67] op_sel_hi:[1,0]
	v_pk_mul_f32 v[48:49], v[48:49], v[66:67] op_sel_hi:[1,0]
	s_and_b64 vcc, exec, s[4:5]
	v_lshrrev_b32_e32 v66, 5, v68
	s_cbranch_vccnz .LBB0_1037
	s_waitcnt vmcnt(0)
	v_mov_b32_e32 v69, v158
	v_mov_b32_e32 v158, v157
	v_mov_b32_e32 v68, v156
	v_pk_mul_f32 v[70:71], v[52:53], v[158:159]
	v_lshl_add_u32 v67, v65, 9, s56
	v_pk_fma_f32 v[70:71], v[60:61], v[68:69], v[70:71] neg_lo:[0,0,1] neg_hi:[0,0,1]
	v_pk_mul_f32 v[68:69], v[52:53], v[68:69]
	v_or_b32_e32 v67, v67, v66
	v_pk_fma_f32 v[72:73], v[60:61], v[158:159], v[68:69]
	v_mov_b32_e32 v69, v154
	v_mov_b32_e32 v154, v153
	v_mov_b32_e32 v68, v152
	v_pk_mul_f32 v[74:75], v[54:55], v[154:155]
	s_nop 0
	v_pk_fma_f32 v[74:75], v[62:63], v[68:69], v[74:75] neg_lo:[0,0,1] neg_hi:[0,0,1]
	v_pk_mul_f32 v[68:69], v[54:55], v[68:69]
	s_nop 0
	v_pk_fma_f32 v[76:77], v[62:63], v[154:155], v[68:69]
	v_mov_b32_e32 v69, v150
	v_mov_b32_e32 v150, v149
	v_mov_b32_e32 v68, v148
	v_pk_mul_f32 v[78:79], v[48:49], v[150:151]
	s_nop 0
	v_pk_fma_f32 v[78:79], v[56:57], v[68:69], v[78:79] neg_lo:[0,0,1] neg_hi:[0,0,1]
	v_pk_mul_f32 v[68:69], v[48:49], v[68:69]
	s_nop 0
	v_pk_fma_f32 v[80:81], v[56:57], v[150:151], v[68:69]
	v_mov_b32_e32 v69, v146
	v_mov_b32_e32 v146, v145
	v_mov_b32_e32 v68, v144
	v_pk_mul_f32 v[82:83], v[50:51], v[146:147]
	s_nop 0
	v_pk_fma_f32 v[82:83], v[58:59], v[68:69], v[82:83] neg_lo:[0,0,1] neg_hi:[0,0,1]
	v_pk_mul_f32 v[68:69], v[50:51], v[68:69]
	s_nop 0
	v_pk_fma_f32 v[84:85], v[58:59], v[146:147], v[68:69]
	v_mad_i64_i32 v[68:69], s[10:11], v67, s54, v[182:183]
	v_lshl_add_u64 v[86:87], v[68:69], 0, v[168:169]
	v_lshl_add_u64 v[88:89], v[178:179], 1, v[86:87]
	v_cvt_pk_bf16_f32 v68, v70, v71
	v_cvt_pk_bf16_f32 v69, v74, v75
	v_cvt_pk_bf16_f32 v70, v78, v79
	v_cvt_pk_bf16_f32 v71, v82, v83
	global_store_dwordx4 v[88:89], v[68:71], off
	v_lshl_add_u64 v[74:75], v[180:181], 1, v[86:87]
	s_mov_b64 s[10:11], 0
	v_cvt_pk_bf16_f32 v68, v72, v73
	v_cvt_pk_bf16_f32 v69, v76, v77
	v_cvt_pk_bf16_f32 v70, v80, v81
	v_cvt_pk_bf16_f32 v71, v84, v85
	global_store_dwordx4 v[74:75], v[68:71], off
.LBB0_1037:
	s_andn2_b64 vcc, exec, s[10:11]
	s_cbranch_vccnz .LBB0_1039
	v_lshl_add_u32 v65, v65, 9, s57
	v_or_b32_e32 v65, v65, v66
	v_mad_i64_i32 v[66:67], s[10:11], v65, s54, v[184:185]
	v_lshl_add_u64 v[66:67], v[66:67], 0, v[168:169]
	v_cvt_pk_bf16_f32 v52, v52, v53
	v_cvt_pk_bf16_f32 v53, v54, v55
	v_cvt_pk_bf16_f32 v54, v48, v49
	v_add_co_u32_e32 v48, vcc, 0xc0000, v66
	v_cvt_pk_bf16_f32 v60, v60, v61
	v_cvt_pk_bf16_f32 v61, v62, v63
	v_cvt_pk_bf16_f32 v62, v56, v57
	v_cvt_pk_bf16_f32 v63, v58, v59
	v_cvt_pk_bf16_f32 v55, v50, v51
	v_addc_co_u32_e32 v49, vcc, 0, v67, vcc
	global_store_dwordx4 v[66:67], v[60:63], off
	global_store_dwordx4 v[48:49], v[52:55], off
.LBB0_1039:
	v_fmamk_f32 v48, v203, 0x3b2aaaab, v198
	v_rsq_f32_e32 v49, v48
	v_and_b32_e32 v51, 0x7ff, v64
	v_ashrrev_i32_e32 v48, 11, v64
	s_mov_b64 s[10:11], -1
	v_mul_f32_e32 v50, 0x3dd53b94, v49
	v_pk_mul_f32 v[46:47], v[46:47], v[50:51] op_sel_hi:[1,0]
	v_pk_mul_f32 v[44:45], v[44:45], v[50:51] op_sel_hi:[1,0]
	v_pk_mul_f32 v[42:43], v[42:43], v[50:51] op_sel_hi:[1,0]
	v_pk_mul_f32 v[40:41], v[40:41], v[50:51] op_sel_hi:[1,0]
	v_pk_mul_f32 v[38:39], v[38:39], v[50:51] op_sel_hi:[1,0]
	v_pk_mul_f32 v[36:37], v[36:37], v[50:51] op_sel_hi:[1,0]
	v_pk_mul_f32 v[34:35], v[34:35], v[50:51] op_sel_hi:[1,0]
	v_pk_mul_f32 v[32:33], v[32:33], v[50:51] op_sel_hi:[1,0]
	s_and_b64 vcc, exec, s[4:5]
	v_lshrrev_b32_e32 v50, 5, v51
	v_lshlrev_b32_e32 v49, 4, v64
	s_cbranch_vccnz .LBB0_1041
	s_waitcnt vmcnt(0)
	v_mov_b32_e32 v53, v142
	v_mov_b32_e32 v142, v141
	v_mov_b32_e32 v52, v140
	v_pk_mul_f32 v[54:55], v[36:37], v[142:143]
	v_lshl_add_u32 v51, v48, 9, s56
	v_pk_fma_f32 v[54:55], v[44:45], v[52:53], v[54:55] neg_lo:[0,0,1] neg_hi:[0,0,1]
	v_pk_mul_f32 v[52:53], v[36:37], v[52:53]
	v_or_b32_e32 v51, v51, v50
	v_pk_fma_f32 v[56:57], v[44:45], v[142:143], v[52:53]
	v_mov_b32_e32 v53, v138
	v_mov_b32_e32 v138, v137
	v_mov_b32_e32 v52, v136
	v_pk_mul_f32 v[58:59], v[38:39], v[138:139]
	v_and_b32_e32 v70, 0x1f0, v49
	v_pk_fma_f32 v[58:59], v[46:47], v[52:53], v[58:59] neg_lo:[0,0,1] neg_hi:[0,0,1]
	v_pk_mul_f32 v[52:53], v[38:39], v[52:53]
	v_mov_b32_e32 v71, v169
	v_pk_fma_f32 v[60:61], v[46:47], v[138:139], v[52:53]
	v_mov_b32_e32 v53, v134
	v_mov_b32_e32 v134, v133
	v_mov_b32_e32 v52, v132
	v_pk_mul_f32 v[62:63], v[32:33], v[134:135]
	s_nop 0
	v_pk_fma_f32 v[62:63], v[40:41], v[52:53], v[62:63] neg_lo:[0,0,1] neg_hi:[0,0,1]
	v_pk_mul_f32 v[52:53], v[32:33], v[52:53]
	s_nop 0
	v_pk_fma_f32 v[64:65], v[40:41], v[134:135], v[52:53]
	v_mov_b32_e32 v53, v130
	v_mov_b32_e32 v130, v129
	v_mov_b32_e32 v52, v128
	v_pk_mul_f32 v[66:67], v[34:35], v[130:131]
	s_nop 0
	v_pk_fma_f32 v[66:67], v[42:43], v[52:53], v[66:67] neg_lo:[0,0,1] neg_hi:[0,0,1]
	v_pk_mul_f32 v[52:53], v[34:35], v[52:53]
	s_nop 0
	v_pk_fma_f32 v[68:69], v[42:43], v[130:131], v[52:53]
	v_mad_i64_i32 v[52:53], s[10:11], v51, s54, v[182:183]
	v_lshl_add_u64 v[70:71], v[52:53], 0, v[70:71]
	v_lshl_add_u64 v[72:73], v[178:179], 1, v[70:71]
	v_cvt_pk_bf16_f32 v52, v54, v55
	v_cvt_pk_bf16_f32 v53, v58, v59
	v_cvt_pk_bf16_f32 v54, v62, v63
	v_cvt_pk_bf16_f32 v55, v66, v67
	global_store_dwordx4 v[72:73], v[52:55], off
	v_lshl_add_u64 v[58:59], v[180:181], 1, v[70:71]
	s_mov_b64 s[10:11], 0
	v_cvt_pk_bf16_f32 v52, v56, v57
	v_cvt_pk_bf16_f32 v53, v60, v61
	v_cvt_pk_bf16_f32 v54, v64, v65
	v_cvt_pk_bf16_f32 v55, v68, v69
	global_store_dwordx4 v[58:59], v[52:55], off
.LBB0_1041:
	s_andn2_b64 vcc, exec, s[10:11]
	s_cbranch_vccnz .LBB0_1043
	v_lshl_add_u32 v48, v48, 9, s57
	v_or_b32_e32 v48, v48, v50
	v_mad_i64_i32 v[50:51], s[10:11], v48, s54, v[184:185]
	v_and_b32_e32 v48, 0x1f0, v49
	v_mov_b32_e32 v49, v169
	v_lshl_add_u64 v[48:49], v[50:51], 0, v[48:49]
	v_cvt_pk_bf16_f32 v36, v36, v37
	v_cvt_pk_bf16_f32 v37, v38, v39
	v_cvt_pk_bf16_f32 v38, v32, v33
	v_add_co_u32_e32 v32, vcc, 0xc0000, v48
	v_cvt_pk_bf16_f32 v44, v44, v45
	v_cvt_pk_bf16_f32 v45, v46, v47
	v_cvt_pk_bf16_f32 v46, v40, v41
	v_cvt_pk_bf16_f32 v47, v42, v43
	v_cvt_pk_bf16_f32 v39, v34, v35
	v_addc_co_u32_e32 v33, vcc, 0, v49, vcc
	global_store_dwordx4 v[48:49], v[44:47], off
	global_store_dwordx4 v[32:33], v[36:39], off

; __device__ __forceinline__ u32x4 pk8(f32x4 a, f32x4 b) { u32x4 w; w.x = pk2(a[0], a[1]); w.y = pk2(a[2], a[3]); w.z = pk2(b[0], b[1]); w.w = pk2(b[2], b[3]); return w; }
;     __device__ __forceinline__ void operator()(const AccT& acc, const Unit& u, int wr, int wc, int fr_, int fq_) const {
;     ...
;             for (int m = 2 * (aim & 1); m < 2 * (aim & 1) + 2; ++m) {
;                 const size_t row = (size_t)ROW_OF(ai, m);
;                 const float sc = QSCALE * __builtin_amdgcn_rsqf(ssv[ai][m] * (1.0f / QLORA) + EPS);
;                 const int b = (int)(row >> 11), s = (int)(row & 2047);
;                 const f32x4 a0 = acc[ai][0][m][0] * sc, a1 = acc[ai][0][m][1] * sc, b0 = acc[ai][1][m][0] * sc, b1 = acc[ai][1][m][1] * sc;
;                 if (pn < 4) {
;                     const int ks = 2 * wc + (fq >> 1), h = fq & 1;
;                     bf16_t* p = QI + ((size_t)((b * 8 + 2 * pn) * 64 + (s >> 5))) * 6144 + (ks * 2 + h) * 256 + (s & 31) * 8;
;                     st16(p, pk8(a0, a1)); st16(p + (size_t)64 * 6144, pk8(b0, b1));
;                 } else {
;                     const int head = 4 * (pn - 4) + wc;
;                     const f32x4 c0 = cs[m][0], c1 = cs[m][1], c2 = cs[m][2], c3 = cs[m][3];
;                     f32x4 o1a, o1b, o2a, o2b;
;                     o1a[0] = a0[0] * c0[0] - b0[0] * c0[1]; o2a[0] = a0[0] * c0[1] + b0[0] * c0[0];
;                     o1a[1] = a0[1] * c0[2] - b0[1] * c0[3]; o2a[1] = a0[1] * c0[3] + b0[1] * c0[2];
;                     o1a[2] = a0[2] * c1[0] - b0[2] * c1[1]; o2a[2] = a0[2] * c1[1] + b0[2] * c1[0];
;                     o1a[3] = a0[3] * c1[2] - b0[3] * c1[3]; o2a[3] = a0[3] * c1[3] + b0[3] * c1[2];
;                     o1b[0] = a1[0] * c2[0] - b1[0] * c2[1]; o2b[0] = a1[0] * c2[1] + b1[0] * c2[0];
;                     o1b[1] = a1[1] * c2[2] - b1[1] * c2[3]; o2b[1] = a1[1] * c2[3] + b1[1] * c2[2];
;                     o1b[2] = a1[2] * c3[0] - b1[2] * c3[1]; o2b[2] = a1[2] * c3[1] + b1[2] * c3[0];
;                     o1b[3] = a1[3] * c3[2] - b1[3] * c3[3]; o2b[3] = a1[3] * c3[3] + b1[3] * c3[2];
;                     bf16_t* p = QI + ((size_t)((b * 8 + head) * 64 + (s >> 5))) * 6144 + (fq & 1) * 256 + (s & 31) * 8;
;                     st16(p + (8 + (fq >> 1)) * 512, pk8(o1a, o1b)); st16(p + (10 + (fq >> 1)) * 512, pk8(o2a, o2b));
;                 }
.LBB0_1045:
	v_fmamk_f32 v33, v202, 0x3b2aaaab, v198
	v_rsq_f32_e32 v35, v33
	v_ashrrev_i32_e32 v33, 11, v34
	v_and_b32_e32 v36, 0x7ff, v34
	s_mov_b64 s[6:7], -1
	v_mul_f32_e32 v34, 0x3dd53b94, v35
	v_pk_mul_f32 v[30:31], v[30:31], v[34:35] op_sel_hi:[1,0]
	v_pk_mul_f32 v[28:29], v[28:29], v[34:35] op_sel_hi:[1,0]
	v_pk_mul_f32 v[26:27], v[26:27], v[34:35] op_sel_hi:[1,0]
	v_pk_mul_f32 v[24:25], v[24:25], v[34:35] op_sel_hi:[1,0]
	v_pk_mul_f32 v[22:23], v[22:23], v[34:35] op_sel_hi:[1,0]
	v_pk_mul_f32 v[20:21], v[20:21], v[34:35] op_sel_hi:[1,0]
	v_pk_mul_f32 v[18:19], v[18:19], v[34:35] op_sel_hi:[1,0]
	v_pk_mul_f32 v[16:17], v[16:17], v[34:35] op_sel_hi:[1,0]
	s_and_b64 vcc, exec, s[4:5]
	v_lshrrev_b32_e32 v34, 5, v36
	s_cbranch_vccnz .LBB0_1047
	s_waitcnt vmcnt(0)
	v_mov_b32_e32 v37, v126
	v_mov_b32_e32 v126, v125
	v_mov_b32_e32 v36, v124
	v_pk_mul_f32 v[38:39], v[20:21], v[126:127]
	v_lshl_add_u32 v35, v33, 9, s56
	v_pk_fma_f32 v[38:39], v[28:29], v[36:37], v[38:39] neg_lo:[0,0,1] neg_hi:[0,0,1]
	v_pk_mul_f32 v[36:37], v[20:21], v[36:37]
	v_or_b32_e32 v35, v35, v34
	v_pk_fma_f32 v[40:41], v[28:29], v[126:127], v[36:37]
	v_mov_b32_e32 v37, v122
	v_mov_b32_e32 v122, v121
	v_mov_b32_e32 v36, v120
	v_pk_mul_f32 v[42:43], v[22:23], v[122:123]
	s_nop 0
	v_pk_fma_f32 v[42:43], v[30:31], v[36:37], v[42:43] neg_lo:[0,0,1] neg_hi:[0,0,1]
	v_pk_mul_f32 v[36:37], v[22:23], v[36:37]
	s_nop 0
	v_pk_fma_f32 v[44:45], v[30:31], v[122:123], v[36:37]
	v_mov_b32_e32 v37, v118
	v_mov_b32_e32 v118, v117
	v_mov_b32_e32 v36, v116
	v_pk_mul_f32 v[46:47], v[16:17], v[118:119]
	s_nop 0
	v_pk_fma_f32 v[46:47], v[24:25], v[36:37], v[46:47] neg_lo:[0,0,1] neg_hi:[0,0,1]
	v_pk_mul_f32 v[36:37], v[16:17], v[36:37]
	s_nop 0
	v_pk_fma_f32 v[48:49], v[24:25], v[118:119], v[36:37]
	v_mov_b32_e32 v37, v114
	v_mov_b32_e32 v114, v113
	v_mov_b32_e32 v36, v112
	v_pk_mul_f32 v[50:51], v[18:19], v[114:115]
	s_nop 0
	v_pk_fma_f32 v[50:51], v[26:27], v[36:37], v[50:51] neg_lo:[0,0,1] neg_hi:[0,0,1]
	v_pk_mul_f32 v[36:37], v[18:19], v[36:37]
	s_nop 0
	v_pk_fma_f32 v[52:53], v[26:27], v[114:115], v[36:37]
	v_mad_i64_i32 v[36:37], s[6:7], v35, s54, v[182:183]
	v_lshl_add_u64 v[54:55], v[36:37], 0, v[168:169]
	v_lshl_add_u64 v[56:57], v[178:179], 1, v[54:55]
	v_cvt_pk_bf16_f32 v36, v38, v39
	v_cvt_pk_bf16_f32 v37, v42, v43
	v_cvt_pk_bf16_f32 v38, v46, v47
	v_cvt_pk_bf16_f32 v39, v50, v51
	global_store_dwordx4 v[56:57], v[36:39], off
	v_lshl_add_u64 v[42:43], v[180:181], 1, v[54:55]
	s_mov_b64 s[6:7], 0
	v_cvt_pk_bf16_f32 v36, v40, v41
	v_cvt_pk_bf16_f32 v37, v44, v45
	v_cvt_pk_bf16_f32 v38, v48, v49
	v_cvt_pk_bf16_f32 v39, v52, v53
	global_store_dwordx4 v[42:43], v[36:39], off
.LBB0_1047:
	s_andn2_b64 vcc, exec, s[6:7]
	s_cbranch_vccnz .LBB0_1049
	v_lshl_add_u32 v33, v33, 9, s57
	v_or_b32_e32 v33, v33, v34
	v_mad_i64_i32 v[34:35], s[6:7], v33, s54, v[184:185]
	v_lshl_add_u64 v[34:35], v[34:35], 0, v[168:169]
	v_cvt_pk_bf16_f32 v20, v20, v21
	v_cvt_pk_bf16_f32 v21, v22, v23
	v_cvt_pk_bf16_f32 v22, v16, v17
	v_add_co_u32_e32 v16, vcc, 0xc0000, v34
	v_cvt_pk_bf16_f32 v28, v28, v29
	v_cvt_pk_bf16_f32 v29, v30, v31
	v_cvt_pk_bf16_f32 v30, v24, v25
	v_cvt_pk_bf16_f32 v31, v26, v27
	v_cvt_pk_bf16_f32 v23, v18, v19
	v_addc_co_u32_e32 v17, vcc, 0, v35, vcc
	global_store_dwordx4 v[34:35], v[28:31], off
	global_store_dwordx4 v[16:17], v[20:23], off
.LBB0_1049:
	v_fmamk_f32 v16, v199, 0x3b2aaaab, v198
	v_rsq_f32_e32 v17, v16
	v_and_b32_e32 v19, 0x7ff, v32
	v_ashrrev_i32_e32 v16, 11, v32
	s_mov_b64 s[6:7], -1
	v_mul_f32_e32 v18, 0x3dd53b94, v17
	v_pk_mul_f32 v[14:15], v[14:15], v[18:19] op_sel_hi:[1,0]
	v_pk_mul_f32 v[12:13], v[12:13], v[18:19] op_sel_hi:[1,0]
	v_pk_mul_f32 v[10:11], v[10:11], v[18:19] op_sel_hi:[1,0]
	v_pk_mul_f32 v[8:9], v[8:9], v[18:19] op_sel_hi:[1,0]
	v_pk_mul_f32 v[6:7], v[6:7], v[18:19] op_sel_hi:[1,0]
	v_pk_mul_f32 v[4:5], v[4:5], v[18:19] op_sel_hi:[1,0]
	v_pk_mul_f32 v[2:3], v[2:3], v[18:19] op_sel_hi:[1,0]
	v_pk_mul_f32 v[0:1], v[0:1], v[18:19] op_sel_hi:[1,0]
	s_and_b64 vcc, exec, s[4:5]
	v_lshrrev_b32_e32 v18, 5, v19
	v_lshlrev_b32_e32 v17, 4, v32
	s_cbranch_vccnz .LBB0_1051
	s_waitcnt vmcnt(0)
	v_mov_b32_e32 v21, v110
	v_mov_b32_e32 v110, v109
	v_mov_b32_e32 v20, v108
	v_pk_mul_f32 v[22:23], v[4:5], v[110:111]
	v_lshl_add_u32 v19, v16, 9, s56
	v_pk_fma_f32 v[22:23], v[12:13], v[20:21], v[22:23] neg_lo:[0,0,1] neg_hi:[0,0,1]
	v_pk_mul_f32 v[20:21], v[4:5], v[20:21]
	v_or_b32_e32 v19, v19, v18
	v_pk_fma_f32 v[24:25], v[12:13], v[110:111], v[20:21]
	v_mov_b32_e32 v21, v106
	v_mov_b32_e32 v106, v105
	v_mov_b32_e32 v20, v104
	v_pk_mul_f32 v[26:27], v[6:7], v[106:107]
	v_and_b32_e32 v168, 0x1f0, v17
	v_pk_fma_f32 v[26:27], v[14:15], v[20:21], v[26:27] neg_lo:[0,0,1] neg_hi:[0,0,1]
	v_pk_mul_f32 v[20:21], v[6:7], v[20:21]
	s_mov_b64 s[6:7], 0
	v_pk_fma_f32 v[28:29], v[14:15], v[106:107], v[20:21]
	v_mov_b32_e32 v21, v102
	v_mov_b32_e32 v102, v101
	v_mov_b32_e32 v20, v100
	v_pk_mul_f32 v[30:31], v[0:1], v[102:103]
	s_nop 0
	v_pk_fma_f32 v[30:31], v[8:9], v[20:21], v[30:31] neg_lo:[0,0,1] neg_hi:[0,0,1]
	v_pk_mul_f32 v[20:21], v[0:1], v[20:21]
	s_nop 0
	v_pk_fma_f32 v[32:33], v[8:9], v[102:103], v[20:21]
	v_mov_b32_e32 v21, v98
	v_mov_b32_e32 v98, v97
	v_mov_b32_e32 v20, v96
	v_pk_mul_f32 v[34:35], v[2:3], v[98:99]
	s_nop 0
	v_pk_fma_f32 v[34:35], v[10:11], v[20:21], v[34:35] neg_lo:[0,0,1] neg_hi:[0,0,1]
	v_pk_mul_f32 v[20:21], v[2:3], v[20:21]
	s_nop 0
	v_pk_fma_f32 v[36:37], v[10:11], v[98:99], v[20:21]
	v_mad_i64_i32 v[20:21], s[4:5], v19, s54, v[182:183]
	v_lshl_add_u64 v[38:39], v[20:21], 0, v[168:169]
	v_lshl_add_u64 v[40:41], v[178:179], 1, v[38:39]
	v_cvt_pk_bf16_f32 v20, v22, v23
	v_cvt_pk_bf16_f32 v21, v26, v27
	v_cvt_pk_bf16_f32 v22, v30, v31
	v_cvt_pk_bf16_f32 v23, v34, v35
	global_store_dwordx4 v[40:41], v[20:23], off
	v_lshl_add_u64 v[26:27], v[180:181], 1, v[38:39]
	s_nop 0
	v_cvt_pk_bf16_f32 v20, v24, v25
	v_cvt_pk_bf16_f32 v21, v28, v29
	v_cvt_pk_bf16_f32 v22, v32, v33
	v_cvt_pk_bf16_f32 v23, v36, v37
	global_store_dwordx4 v[26:27], v[20:23], off
.LBB0_1051:
	s_andn2_b64 vcc, exec, s[6:7]
	s_cbranch_vccnz .LBB0_1053
	v_lshl_add_u32 v16, v16, 9, s57
	v_or_b32_e32 v16, v16, v18
	v_mad_i64_i32 v[18:19], s[4:5], v16, s54, v[184:185]
	v_and_b32_e32 v168, 0x1f0, v17
	v_lshl_add_u64 v[16:17], v[18:19], 0, v[168:169]
	v_cvt_pk_bf16_f32 v4, v4, v5
	v_cvt_pk_bf16_f32 v5, v6, v7
	v_cvt_pk_bf16_f32 v6, v0, v1
	v_add_co_u32_e32 v0, vcc, 0xc0000, v16
	v_cvt_pk_bf16_f32 v12, v12, v13
	v_cvt_pk_bf16_f32 v13, v14, v15
	v_cvt_pk_bf16_f32 v14, v8, v9
	v_cvt_pk_bf16_f32 v15, v10, v11
	v_cvt_pk_bf16_f32 v7, v2, v3
	v_addc_co_u32_e32 v1, vcc, 0, v17, vcc
	global_store_dwordx4 v[16:17], v[12:15], off
	global_store_dwordx4 v[0:1], v[4:7], off
